# RWKV scan helpers: bonus (r.k.r_k) duty rotated over the four workgroups of a (batch, head) by token block instead of always the dir0/half0 workgroup (load balance)
# speedup vs baseline: 1.0043x; 1.0019x over previous
;     __device__ __forceinline__ bf16* R(int i) const { return (bf16*)(ws + OFF_R0 + (size_t)i * RSZ); }
; __device__ __forceinline__ void phase_rwkv_scan(const Fr& F, int jr) {
;     ...
;     const int bxs = (int)blockIdx.x, bxcd = (gridDim.x == 256) ? (bxs & 7) * 32 + (bxs >> 3) : bxs;
;     for (int task = bxcd; task < 256; task += gridDim.x) {
;         const int half = task & 1, h = (task >> 1) & 15, b = (task >> 5) & 3, s = task >> 7;
;         bf16* Yb = F.R(s);
;         const float* w0 = F.a->in[9] + (size_t)(jr * 2 + s) * D + h * 64; const float* a0 = F.a->in[12] + (size_t)(jr * 2 + s) * D + h * 64;
;         const float* kkw = F.a->in[15] + (size_t)jr * D + h * 64; const float* kaw = F.a->in[16] + (size_t)jr * D + h * 64;
;         f32x2 S01 = {0.f, 0.f}, S23 = {0.f, 0.f};
;         const int ks = 4 * l15, rloc = 4 * wave + lq;
;         const int pt = wave & 3, ht0 = (wave >> 2) * 2;
;         const int p1 = pt * 16 + l15;
;         const int p2 = tid >> 3, j8 = tid & 7, hk0 = 8 * j8;
;         bf16x8 Bw[2][2], Ba[2][2]; float w0v[2], a0v[2];
; #pragma unroll
;         for (int hh = 0; hh < 2; ++hh) { const int hk = (ht0 + hh) * 16 + l15, e = h * 64 + hk; w0v[hh] = w0[hk]; a0v[hh] = a0[hk];
; #pragma unroll
;             for (int kst = 0; kst < 2; ++kst) { Bw[hh][kst] = *(const bf16x8*)(L2T + ((size_t)s * D + e) * 64 + 32 * kst + 8 * lq); Ba[hh][kst] = *(const bf16x8*)(L2T + ((size_t)(2 + s) * D + e) * 64 + 32 * kst + 8 * lq); } }
;         float kkc[8], kac[8], rkc[8];
; #pragma unroll
;         for (int i = 0; i < 8; ++i) { kkc[i] = kkw[hk0 + i]; kac[i] = kaw[hk0 + i]; rkc[i] = F.a->in[17][(size_t)jr * D + h * 64 + hk0 + i]; }
;         float* Bon = (float*)(F.ws + OFF_R0 + 6 * RSZ + 16 * MiB);
;         bf16x8 Aw[2], Aa[2]; u32x4 kw, rw; u32x2 vw;
;         {   const size_t row1 = (size_t)b * TB + tokof(s, p1), row2 = (size_t)b * TB + tokof(s, p2);
; #pragma unroll
;             for (int kst = 0; kst < 2; ++kst) { Aw[kst] = *(const bf16x8*)(LM + row1 * 256 + 64 * s + 32 * kst + 8 * lq); Aa[kst] = *(const bf16x8*)(LM + row1 * 256 + 128 + 64 * s + 32 * kst + 8 * lq); }
;             kw = *(const u32x4*)(Kb + row2 * D + h * 64 + hk0); rw = *(const u32x4*)(Rb + row2 * D + h * 64 + hk0); vw = *(const u32x2*)(Vb + row2 * D + h * 64 + 32 * half + 4 * j8); }
.Lrw0_hdir0:
	s_mul_i32 s16, s7, 0x1100
	v_lshlrev_b32_e32 v221, 4, v217
	s_lshl_b32 s17, s15, 6
	v_lshl_add_u32 v219, v217, 3, s17
	s_xor_b32 s18, s17, 64
	v_lshl_add_u32 v220, v217, 3, s18
	s_lshl_b32 s17, s15, 7
	v_mul_u32_u24_e32 v197, 0x110, v216
	v_add_u32_e32 v197, s17, v197
	v_lshl_add_u32 v222, v217, 4, v197
	v_lshrrev_b32_e32 v201, 1, v216
	v_mul_u32_u24_e32 v201, 0x210, v201
	v_and_b32_e32 v203, 1, v216
	v_lshl_add_u32 v201, v203, 3, v201
	s_lshl_b32 s18, s15, 8
	v_lshl_add_u32 v203, v217, 6, s18
	v_add_u32_e32 v223, v201, v203
	s_lshl_b32 s17, s6, 7
	s_add_u32 s20, s26, 0xde00000
	s_addc_u32 s21, s27, 0
	s_add_u32 s20, s20, s17
	s_addc_u32 s21, s21, 0
	s_lshl_b32 s17, s8, 7
	s_add_u32 s22, s26, 0xbc00000
	s_addc_u32 s23, s27, 0
	s_add_u32 s22, s22, s17
	s_addc_u32 s23, s23, 0
	s_add_u32 s24, s26, 0x9a00000
	s_addc_u32 s25, s27, 0
	s_add_u32 s24, s24, s17
	s_addc_u32 s25, s25, 0
	s_lshl_b32 s18, s9, 6
	s_add_i32 s17, s17, s18
	s_lshl_b32 s18, s15, 5
	s_add_i32 s17, s17, s18
	s_add_u32 s42, s26, 0x5600000
	s_addc_u32 s43, s27, 0
	s_add_u32 s42, s42, s17
	s_addc_u32 s43, s43, 0
	s_lshl_b32 s17, s8, 2
	s_add_u32 s44, s26, 0xee00000
	s_addc_u32 s45, s27, 0
	s_add_u32 s44, s44, s17
	s_addc_u32 s45, s45, 0
	s_cmp_eq_u32 s15, 0
	s_cselect_b32 s58, 1, 0
	s_xor_b32 s59, s6, s9
	s_load_dwordx2 s[46:47], s[0:1], 0x48
	s_load_dwordx2 s[48:49], s[0:1], 0x60
	s_load_dwordx2 s[50:51], s[0:1], 0x78
	s_load_dwordx2 s[52:53], s[0:1], 0x80
	s_load_dwordx2 s[54:55], s[0:1], 0x88
	s_lshl_b32 s17, s8, 8
	s_lshl_b32 s18, s15, 7
	s_add_i32 s19, s17, s18
	v_lshl_add_u32 v198, v217, 4, s19
	s_xor_b32 s18, s18, 128
	s_add_i32 s19, s17, s18
	v_lshl_add_u32 v199, v217, 4, s19
	s_waitcnt lgkmcnt(0)
	s_lshl_b32 s17, s6, 12
	s_add_u32 s46, s46, s17
	s_addc_u32 s47, s47, 0
	s_add_u32 s48, s48, s17
	s_addc_u32 s49, s49, 0
	global_load_dwordx4 v[32:35], v198, s[46:47] offset:0
	global_load_dwordx4 v[40:43], v198, s[48:49] offset:0
	global_load_dwordx4 v[64:67], v198, s[52:53] offset:0
	global_load_dwordx4 v[36:39], v198, s[46:47] offset:64
	global_load_dwordx4 v[44:47], v198, s[48:49] offset:64
	global_load_dwordx4 v[68:71], v198, s[52:53] offset:64
	global_load_dwordx4 v[48:51], v198, s[50:51] offset:0
	global_load_dwordx4 v[72:75], v198, s[54:55] offset:0
	global_load_dwordx4 v[52:55], v198, s[50:51] offset:64
	global_load_dwordx4 v[76:79], v198, s[54:55] offset:64
	global_load_dwordx4 v[56:59], v199, s[50:51] offset:0
	global_load_dwordx4 v[80:83], v199, s[54:55] offset:0
	global_load_dwordx4 v[60:63], v199, s[50:51] offset:64
	global_load_dwordx4 v[84:87], v199, s[54:55] offset:64
	s_lshl_b32 s17, s8, 6
	s_lshl_b32 s18, s15, 5
	s_add_i32 s17, s17, s18
	v_add_u32_e32 v200, s17, v196
	v_lshlrev_b32_e32 v200, 7, v200
	v_add_u32_e32 v200, v200, v221
	s_lshl_b32 s17, s6, 17
	s_add_u32 s46, s26, 0x200000
	s_addc_u32 s47, s27, 0
	s_add_u32 s46, s46, s17
	s_addc_u32 s47, s47, 0
	s_add_u32 s48, s46, 0x40000
	s_addc_u32 s49, s47, 0
	global_load_dwordx4 v[0:3], v200, s[46:47] offset:0
	global_load_dwordx4 v[16:19], v200, s[48:49] offset:0
	global_load_dwordx4 v[4:7], v200, s[46:47] offset:64
	global_load_dwordx4 v[20:23], v200, s[48:49] offset:64
	global_load_dwordx4 v[8:11], v200, s[46:47] offset:2048
	global_load_dwordx4 v[24:27], v200, s[48:49] offset:2048
	global_load_dwordx4 v[12:15], v200, s[46:47] offset:2112
	global_load_dwordx4 v[28:31], v200, s[48:49] offset:2112
	s_mov_b32 s10, 0
	s_mov_b32 s11, 0
	s_lshl_b32 s17, s10, 5
	s_cmp_lt_u32 s10, 8
	s_movk_i32 s18, 0x11ff
	s_cselect_b32 s18, 0xff, s18
	s_sub_i32 s18, s18, s17
	s_cmp_eq_u32 s6, 0
	s_cselect_b32 s17, s17, s18
	s_add_i32 s17, s17, s16
	v_add_u32_e32 v231, s17, v218
	v_lshl_add_u32 v226, v231, 9, v221
	v_lshl_add_u32 v227, v231, 11, v219
	v_lshl_add_u32 v228, v231, 11, v220
	v_lshlrev_b32_e32 v229, 3, v217
	v_lshl_add_u32 v229, v231, 11, v229
	v_lshlrev_b32_e32 v230, 6, v231
	global_load_dwordx4 v[88:91], v226, s[20:21]
	global_load_dwordx4 v[92:95], v226, s[20:21] offset:64
	global_load_dwordx4 v[96:99], v226, s[20:21] offset:256
	global_load_dwordx4 v[100:103], v226, s[20:21] offset:320
	global_load_dwordx2 v[104:105], v227, s[22:23] offset:0
	global_load_dwordx2 v[106:107], v227, s[22:23] offset:32
	global_load_dwordx2 v[108:109], v228, s[22:23] offset:0
	global_load_dwordx2 v[110:111], v228, s[22:23] offset:32
	global_load_dwordx2 v[112:113], v227, s[24:25] offset:0
	global_load_dwordx2 v[114:115], v227, s[24:25] offset:32
	global_load_dwordx2 v[116:117], v228, s[24:25] offset:0
	global_load_dwordx2 v[118:119], v228, s[24:25] offset:32
	global_load_dwordx2 v[120:121], v229, s[42:43]
	v_mov_b32_e32 v224, v222
	v_mov_b32_e32 v225, v223
	v_mov_b32_e32 v202, v230
	s_and_b32 s17, s10, 3
	s_cmp_eq_u32 s17, s59
	s_cselect_b32 s32, s58, 0
	s_waitcnt vmcnt(0)
; __device__ __forceinline__ float sigm(float x) { return __builtin_amdgcn_rcpf(1.f + __expf(-x)); }
; template <int CTRL> __device__ __forceinline__ float dppf(float x) { return __builtin_bit_cast(float, __builtin_amdgcn_update_dpp(0, __builtin_bit_cast(int, x), CTRL, 0xF, 0xF, false)); }
; #define LDS_BAR() asm volatile("s_waitcnt lgkmcnt(0)\n\ts_barrier" ::: "memory")
; __device__ __forceinline__ void phase_rwkv_scan(const Fr& F, int jr) {
;     ...
;                 for (int kst = 0; kst < 2; ++kst) { cw = __builtin_amdgcn_mfma_f32_16x16x32_bf16(Aw[kst], Bw[hh][kst], cw, 0, 0, 0); ca = __builtin_amdgcn_mfma_f32_16x16x32_bf16(Aa[kst], Ba[hh][kst], ca, 0, 0, 0); }
; #pragma unroll
;                 for (int reg = 0; reg < 4; ++reg) { const int pp = pt * 16 + lq * 4 + reg;
;                     Wv[pp * 64 + hk] = __expf(-0.60653066f * sigm(w0v[hh] + cw[reg]));
;                     Av[pp * 64 + hk] = sigm(a0v[hh] + ca[reg]); }
;             }
;             LDS_BAR();
;             {
;                 const float kr[8] = {lo_bf(kw.x), hi_bf(kw.x), lo_bf(kw.y), hi_bf(kw.y), lo_bf(kw.z), hi_bf(kw.z), lo_bf(kw.w), hi_bf(kw.w)};
;                 const float rr[8] = {lo_bf(rw.x), hi_bf(rw.x), lo_bf(rw.y), hi_bf(rw.y), lo_bf(rw.z), hi_bf(rw.z), lo_bf(rw.w), hi_bf(rw.w)};
;                 float kq[8]; float ss = 0.f, bon = 0.f;
; #pragma unroll
;                 for (int i = 0; i < 8; ++i) { kq[i] = kr[i] * kkc[i]; ss += kq[i] * kq[i]; bon += rr[i] * kr[i] * rkc[i]; }
;                 ss += dppf<0xB1>(ss); ss += dppf<0x4E>(ss); ss += dppf<0x141>(ss); bon += dppf<0xB1>(bon); bon += dppf<0x4E>(bon); bon += dppf<0x141>(bon);
;                 if (s == 0 && half == 0 && j8 == 0) Bon[((size_t)b * TB + tokof(s, chunk * 64 + p2)) * 16 + h] = bon;
	v_mfma_f32_16x16x32_bf16 v[136:139], v[0:3], v[88:91], 0
	v_mfma_f32_16x16x32_bf16 v[136:139], v[4:7], v[92:95], v[136:139]
	v_mfma_f32_16x16x32_bf16 v[140:143], v[8:11], v[88:91], 0
	v_mfma_f32_16x16x32_bf16 v[140:143], v[12:15], v[92:95], v[140:143]
	v_mfma_f32_16x16x32_bf16 v[144:147], v[16:19], v[96:99], 0
	v_mfma_f32_16x16x32_bf16 v[144:147], v[20:23], v[100:103], v[144:147]
	v_mfma_f32_16x16x32_bf16 v[148:151], v[24:27], v[96:99], 0
	v_mfma_f32_16x16x32_bf16 v[148:151], v[28:31], v[100:103], v[148:151]
	v_lshlrev_b32_e32 v152, 16, v104
	v_and_b32_e32 v153, 0xffff0000, v104
	v_lshlrev_b32_e32 v154, 16, v105
	v_and_b32_e32 v155, 0xffff0000, v105
	v_lshlrev_b32_e32 v156, 16, v106
	v_and_b32_e32 v157, 0xffff0000, v106
	v_lshlrev_b32_e32 v158, 16, v107
	v_and_b32_e32 v159, 0xffff0000, v107
	v_lshlrev_b32_e32 v160, 16, v108
	v_and_b32_e32 v161, 0xffff0000, v108
	v_lshlrev_b32_e32 v162, 16, v109
	v_and_b32_e32 v163, 0xffff0000, v109
	v_lshlrev_b32_e32 v164, 16, v110
	v_and_b32_e32 v165, 0xffff0000, v110
	v_lshlrev_b32_e32 v166, 16, v111
	v_and_b32_e32 v167, 0xffff0000, v111
	v_lshlrev_b32_e32 v168, 16, v112
	v_and_b32_e32 v169, 0xffff0000, v112
	v_lshlrev_b32_e32 v170, 16, v113
	v_and_b32_e32 v171, 0xffff0000, v113
	v_lshlrev_b32_e32 v172, 16, v114
	v_and_b32_e32 v173, 0xffff0000, v114
	v_lshlrev_b32_e32 v174, 16, v115
	v_and_b32_e32 v175, 0xffff0000, v115
	v_lshlrev_b32_e32 v192, 16, v120
	v_and_b32_e32 v193, 0xffff0000, v120
	v_lshlrev_b32_e32 v194, 16, v121
	v_and_b32_e32 v195, 0xffff0000, v121
	v_pk_mul_f32 v[176:177], v[152:153], v[48:49]
	v_pk_mul_f32 v[178:179], v[154:155], v[50:51]
	v_pk_mul_f32 v[180:181], v[156:157], v[52:53]
	v_pk_mul_f32 v[182:183], v[158:159], v[54:55]
	v_pk_mul_f32 v[184:185], v[160:161], v[56:57]
	v_pk_mul_f32 v[186:187], v[162:163], v[58:59]
	v_pk_mul_f32 v[188:189], v[164:165], v[60:61]
	v_pk_mul_f32 v[190:191], v[166:167], v[62:63]
	v_pk_mul_f32 v[196:197], v[176:177], v[176:177]
	v_pk_mul_f32 v[198:199], v[178:179], v[178:179]
	v_pk_fma_f32 v[196:197], v[180:181], v[180:181], v[196:197]
	v_pk_fma_f32 v[198:199], v[182:183], v[182:183], v[198:199]
	v_pk_fma_f32 v[196:197], v[184:185], v[184:185], v[196:197]
	v_pk_fma_f32 v[198:199], v[186:187], v[186:187], v[198:199]
	v_pk_fma_f32 v[196:197], v[188:189], v[188:189], v[196:197]
	v_pk_fma_f32 v[198:199], v[190:191], v[190:191], v[198:199]
	s_nop 0
	v_pk_add_f32 v[196:197], v[196:197], v[198:199]
	s_cmp_eq_u32 s32, 0
	s_cbranch_scc1 .Lrw0_hnbc0
	v_mul_f32_e32 v208, v168, v152
	v_mul_f32_e32 v209, v169, v153
	v_mul_f32_e32 v210, v170, v154
	v_mul_f32_e32 v211, v171, v155
	v_mul_f32_e32 v234, v72, v208
	v_fmac_f32_e32 v234, v73, v209
	v_fmac_f32_e32 v234, v74, v210
	v_fmac_f32_e32 v234, v75, v211
	v_mul_f32_e32 v208, v172, v156
	v_mul_f32_e32 v209, v173, v157
	v_mul_f32_e32 v210, v174, v158
	v_mul_f32_e32 v211, v175, v159
	v_fmac_f32_e32 v234, v76, v208
	v_fmac_f32_e32 v234, v77, v209
	v_fmac_f32_e32 v234, v78, v210
	v_fmac_f32_e32 v234, v79, v211
	v_lshlrev_b32_e32 v204, 16, v116
	v_and_b32_e32 v205, 0xffff0000, v116
	v_lshlrev_b32_e32 v206, 16, v117
	v_and_b32_e32 v207, 0xffff0000, v117
	v_mul_f32_e32 v208, v204, v160
	v_mul_f32_e32 v209, v205, v161
	v_mul_f32_e32 v210, v206, v162
	v_mul_f32_e32 v211, v207, v163
	v_fmac_f32_e32 v234, v80, v208
	v_fmac_f32_e32 v234, v81, v209
	v_fmac_f32_e32 v234, v82, v210
	v_fmac_f32_e32 v234, v83, v211
	v_lshlrev_b32_e32 v204, 16, v118
	v_and_b32_e32 v205, 0xffff0000, v118
	v_lshlrev_b32_e32 v206, 16, v119
	v_and_b32_e32 v207, 0xffff0000, v119
	v_mul_f32_e32 v208, v204, v164
	v_mul_f32_e32 v209, v205, v165
	v_mul_f32_e32 v210, v206, v166
	v_mul_f32_e32 v211, v207, v167
	v_fmac_f32_e32 v234, v84, v208
	v_fmac_f32_e32 v234, v85, v209
	v_fmac_f32_e32 v234, v86, v210
	v_fmac_f32_e32 v234, v87, v211

; __device__ __forceinline__ float sigm(float x) { return __builtin_amdgcn_rcpf(1.f + __expf(-x)); }
; template <int CTRL> __device__ __forceinline__ float dppf(float x) { return __builtin_bit_cast(float, __builtin_amdgcn_update_dpp(0, __builtin_bit_cast(int, x), CTRL, 0xF, 0xF, false)); }
; #define LDS_BAR() asm volatile("s_waitcnt lgkmcnt(0)\n\ts_barrier" ::: "memory")
; __device__ __forceinline__ void phase_rwkv_scan(const Fr& F, int jr) {
;     ...
;         for (int chunk = 0; chunk < TB / 64; ++chunk) {
; #pragma unroll
;             for (int hh = 0; hh < 2; ++hh) {
;                 const int hk = (ht0 + hh) * 16 + l15;
;                 f32x4 cw = {0.f, 0.f, 0.f, 0.f}, ca = {0.f, 0.f, 0.f, 0.f};
; #pragma unroll
;                 for (int kst = 0; kst < 2; ++kst) { cw = __builtin_amdgcn_mfma_f32_16x16x32_bf16(Aw[kst], Bw[hh][kst], cw, 0, 0, 0); ca = __builtin_amdgcn_mfma_f32_16x16x32_bf16(Aa[kst], Ba[hh][kst], ca, 0, 0, 0); }
; #pragma unroll
;                 for (int reg = 0; reg < 4; ++reg) { const int pp = pt * 16 + lq * 4 + reg;
;                     Wv[pp * 64 + hk] = __expf(-0.60653066f * sigm(w0v[hh] + cw[reg]));
;                     Av[pp * 64 + hk] = sigm(a0v[hh] + ca[reg]); }
;             }
;             LDS_BAR();
;             {
;                 const float kr[8] = {lo_bf(kw.x), hi_bf(kw.x), lo_bf(kw.y), hi_bf(kw.y), lo_bf(kw.z), hi_bf(kw.z), lo_bf(kw.w), hi_bf(kw.w)};
;                 const float rr[8] = {lo_bf(rw.x), hi_bf(rw.x), lo_bf(rw.y), hi_bf(rw.y), lo_bf(rw.z), hi_bf(rw.z), lo_bf(rw.w), hi_bf(rw.w)};
;                 float kq[8]; float ss = 0.f, bon = 0.f;
; #pragma unroll
;                 for (int i = 0; i < 8; ++i) { kq[i] = kr[i] * kkc[i]; ss += kq[i] * kq[i]; bon += rr[i] * kr[i] * rkc[i]; }
;                 ss += dppf<0xB1>(ss); ss += dppf<0x4E>(ss); ss += dppf<0x141>(ss); bon += dppf<0xB1>(bon); bon += dppf<0x4E>(bon); bon += dppf<0x141>(bon);
;                 if (s == 0 && half == 0 && j8 == 0) Bon[((size_t)b * TB + tokof(s, chunk * 64 + p2)) * 16 + h] = bon;
.Lrw0_hhc:
	s_cmp_lt_u32 s10, 136
	s_cbranch_scc0 .Lrw0_hlast
	s_xor_b32 s11, s11, 0xcc00
	v_add_u32_e32 v224, s11, v222
	v_add_u32_e32 v225, s11, v223
	v_mov_b32_e32 v202, v230
	s_and_b32 s17, s10, 3
	s_cmp_eq_u32 s17, s59
	s_cselect_b32 s32, s58, 0
	s_waitcnt vmcnt(0)
	v_mfma_f32_16x16x32_bf16 v[136:139], v[0:3], v[88:91], 0
	v_mfma_f32_16x16x32_bf16 v[136:139], v[4:7], v[92:95], v[136:139]
	v_mfma_f32_16x16x32_bf16 v[140:143], v[8:11], v[88:91], 0
	v_mfma_f32_16x16x32_bf16 v[140:143], v[12:15], v[92:95], v[140:143]
	v_mfma_f32_16x16x32_bf16 v[144:147], v[16:19], v[96:99], 0
	v_mfma_f32_16x16x32_bf16 v[144:147], v[20:23], v[100:103], v[144:147]
	v_mfma_f32_16x16x32_bf16 v[148:151], v[24:27], v[96:99], 0
	v_mfma_f32_16x16x32_bf16 v[148:151], v[28:31], v[100:103], v[148:151]
	v_lshlrev_b32_e32 v152, 16, v104
	v_and_b32_e32 v153, 0xffff0000, v104
	v_lshlrev_b32_e32 v154, 16, v105
	v_and_b32_e32 v155, 0xffff0000, v105
	v_lshlrev_b32_e32 v156, 16, v106
	v_and_b32_e32 v157, 0xffff0000, v106
	v_lshlrev_b32_e32 v158, 16, v107
	v_and_b32_e32 v159, 0xffff0000, v107
	v_lshlrev_b32_e32 v160, 16, v108
	v_and_b32_e32 v161, 0xffff0000, v108
	v_lshlrev_b32_e32 v162, 16, v109
	v_and_b32_e32 v163, 0xffff0000, v109
	v_lshlrev_b32_e32 v164, 16, v110
	v_and_b32_e32 v165, 0xffff0000, v110
	v_lshlrev_b32_e32 v166, 16, v111
	v_and_b32_e32 v167, 0xffff0000, v111
	v_lshlrev_b32_e32 v168, 16, v112
	v_and_b32_e32 v169, 0xffff0000, v112
	v_lshlrev_b32_e32 v170, 16, v113
	v_and_b32_e32 v171, 0xffff0000, v113
	v_lshlrev_b32_e32 v172, 16, v114
	v_and_b32_e32 v173, 0xffff0000, v114
	v_lshlrev_b32_e32 v174, 16, v115
	v_and_b32_e32 v175, 0xffff0000, v115
	v_lshlrev_b32_e32 v192, 16, v120
	v_and_b32_e32 v193, 0xffff0000, v120
	v_lshlrev_b32_e32 v194, 16, v121
	v_and_b32_e32 v195, 0xffff0000, v121
	v_pk_mul_f32 v[176:177], v[152:153], v[48:49]
	v_pk_mul_f32 v[178:179], v[154:155], v[50:51]
	v_pk_mul_f32 v[180:181], v[156:157], v[52:53]
	v_pk_mul_f32 v[182:183], v[158:159], v[54:55]
	v_pk_mul_f32 v[184:185], v[160:161], v[56:57]
	v_pk_mul_f32 v[186:187], v[162:163], v[58:59]
	v_pk_mul_f32 v[188:189], v[164:165], v[60:61]
	v_pk_mul_f32 v[190:191], v[166:167], v[62:63]
	v_pk_mul_f32 v[196:197], v[176:177], v[176:177]
	v_pk_mul_f32 v[198:199], v[178:179], v[178:179]
	v_pk_fma_f32 v[196:197], v[180:181], v[180:181], v[196:197]
	v_pk_fma_f32 v[198:199], v[182:183], v[182:183], v[198:199]
	v_pk_fma_f32 v[196:197], v[184:185], v[184:185], v[196:197]
	v_pk_fma_f32 v[198:199], v[186:187], v[186:187], v[198:199]
	v_pk_fma_f32 v[196:197], v[188:189], v[188:189], v[196:197]
	v_pk_fma_f32 v[198:199], v[190:191], v[190:191], v[198:199]
	s_nop 0
	v_pk_add_f32 v[196:197], v[196:197], v[198:199]
	s_cmp_eq_u32 s32, 0
	s_cbranch_scc1 .Lrw0_hnbc1
	v_mul_f32_e32 v208, v168, v152
	v_mul_f32_e32 v209, v169, v153
	v_mul_f32_e32 v210, v170, v154
	v_mul_f32_e32 v211, v171, v155
	v_mul_f32_e32 v234, v72, v208
	v_fmac_f32_e32 v234, v73, v209
	v_fmac_f32_e32 v234, v74, v210
	v_fmac_f32_e32 v234, v75, v211
	v_mul_f32_e32 v208, v172, v156
	v_mul_f32_e32 v209, v173, v157
	v_mul_f32_e32 v210, v174, v158
	v_mul_f32_e32 v211, v175, v159
	v_fmac_f32_e32 v234, v76, v208
	v_fmac_f32_e32 v234, v77, v209
	v_fmac_f32_e32 v234, v78, v210
	v_fmac_f32_e32 v234, v79, v211
	v_lshlrev_b32_e32 v204, 16, v116
	v_and_b32_e32 v205, 0xffff0000, v116
	v_lshlrev_b32_e32 v206, 16, v117
	v_and_b32_e32 v207, 0xffff0000, v117
	v_mul_f32_e32 v208, v204, v160
	v_mul_f32_e32 v209, v205, v161
	v_mul_f32_e32 v210, v206, v162
	v_mul_f32_e32 v211, v207, v163
	v_fmac_f32_e32 v234, v80, v208
	v_fmac_f32_e32 v234, v81, v209
	v_fmac_f32_e32 v234, v82, v210
	v_fmac_f32_e32 v234, v83, v211
	v_lshlrev_b32_e32 v204, 16, v118
	v_and_b32_e32 v205, 0xffff0000, v118
	v_lshlrev_b32_e32 v206, 16, v119
	v_and_b32_e32 v207, 0xffff0000, v119
	v_mul_f32_e32 v208, v204, v164
	v_mul_f32_e32 v209, v205, v165
	v_mul_f32_e32 v210, v206, v166
	v_mul_f32_e32 v211, v207, v167
	v_fmac_f32_e32 v234, v84, v208
	v_fmac_f32_e32 v234, v85, v209
	v_fmac_f32_e32 v234, v86, v210
	v_fmac_f32_e32 v234, v87, v211

;     __device__ __forceinline__ bf16* R(int i) const { return (bf16*)(ws + OFF_R0 + (size_t)i * RSZ); }
; __device__ __forceinline__ void phase_rwkv_scan(const Fr& F, int jr) {
;     ...
;     const int bxs = (int)blockIdx.x, bxcd = (gridDim.x == 256) ? (bxs & 7) * 32 + (bxs >> 3) : bxs;
;     for (int task = bxcd; task < 256; task += gridDim.x) {
;         const int half = task & 1, h = (task >> 1) & 15, b = (task >> 5) & 3, s = task >> 7;
;         bf16* Yb = F.R(s);
;         const float* w0 = F.a->in[9] + (size_t)(jr * 2 + s) * D + h * 64; const float* a0 = F.a->in[12] + (size_t)(jr * 2 + s) * D + h * 64;
;         const float* kkw = F.a->in[15] + (size_t)jr * D + h * 64; const float* kaw = F.a->in[16] + (size_t)jr * D + h * 64;
;         f32x2 S01 = {0.f, 0.f}, S23 = {0.f, 0.f};
;         const int ks = 4 * l15, rloc = 4 * wave + lq;
;         const int pt = wave & 3, ht0 = (wave >> 2) * 2;
;         const int p1 = pt * 16 + l15;
;         const int p2 = tid >> 3, j8 = tid & 7, hk0 = 8 * j8;
;         bf16x8 Bw[2][2], Ba[2][2]; float w0v[2], a0v[2];
; #pragma unroll
;         for (int hh = 0; hh < 2; ++hh) { const int hk = (ht0 + hh) * 16 + l15, e = h * 64 + hk; w0v[hh] = w0[hk]; a0v[hh] = a0[hk];
; #pragma unroll
;             for (int kst = 0; kst < 2; ++kst) { Bw[hh][kst] = *(const bf16x8*)(L2T + ((size_t)s * D + e) * 64 + 32 * kst + 8 * lq); Ba[hh][kst] = *(const bf16x8*)(L2T + ((size_t)(2 + s) * D + e) * 64 + 32 * kst + 8 * lq); } }
;         float kkc[8], kac[8], rkc[8];
; #pragma unroll
;         for (int i = 0; i < 8; ++i) { kkc[i] = kkw[hk0 + i]; kac[i] = kaw[hk0 + i]; rkc[i] = F.a->in[17][(size_t)jr * D + h * 64 + hk0 + i]; }
;         float* Bon = (float*)(F.ws + OFF_R0 + 6 * RSZ + 16 * MiB);
;         bf16x8 Aw[2], Aa[2]; u32x4 kw, rw; u32x2 vw;
;         {   const size_t row1 = (size_t)b * TB + tokof(s, p1), row2 = (size_t)b * TB + tokof(s, p2);
; #pragma unroll
;             for (int kst = 0; kst < 2; ++kst) { Aw[kst] = *(const bf16x8*)(LM + row1 * 256 + 64 * s + 32 * kst + 8 * lq); Aa[kst] = *(const bf16x8*)(LM + row1 * 256 + 128 + 64 * s + 32 * kst + 8 * lq); }
;             kw = *(const u32x4*)(Kb + row2 * D + h * 64 + hk0); rw = *(const u32x4*)(Rb + row2 * D + h * 64 + hk0); vw = *(const u32x2*)(Vb + row2 * D + h * 64 + 32 * half + 4 * j8); }
.Lrw3_hdir0:
	s_mul_i32 s16, s7, 0x1100
	v_lshlrev_b32_e32 v221, 4, v217
	s_lshl_b32 s17, s15, 6
	v_lshl_add_u32 v219, v217, 3, s17
	s_xor_b32 s18, s17, 64
	v_lshl_add_u32 v220, v217, 3, s18
	s_lshl_b32 s17, s15, 7
	v_mul_u32_u24_e32 v197, 0x110, v216
	v_add_u32_e32 v197, s17, v197
	v_lshl_add_u32 v222, v217, 4, v197
	v_lshrrev_b32_e32 v201, 1, v216
	v_mul_u32_u24_e32 v201, 0x210, v201
	v_and_b32_e32 v203, 1, v216
	v_lshl_add_u32 v201, v203, 3, v201
	s_lshl_b32 s18, s15, 8
	v_lshl_add_u32 v203, v217, 6, s18
	v_add_u32_e32 v223, v201, v203
	s_lshl_b32 s17, s6, 7
	s_add_u32 s20, s26, 0xde00000
	s_addc_u32 s21, s27, 0
	s_add_u32 s20, s20, s17
	s_addc_u32 s21, s21, 0
	s_lshl_b32 s17, s8, 7
	s_add_u32 s22, s26, 0xbc00000
	s_addc_u32 s23, s27, 0
	s_add_u32 s22, s22, s17
	s_addc_u32 s23, s23, 0
	s_add_u32 s24, s26, 0x9a00000
	s_addc_u32 s25, s27, 0
	s_add_u32 s24, s24, s17
	s_addc_u32 s25, s25, 0
	s_lshl_b32 s18, s9, 6
	s_add_i32 s17, s17, s18
	s_lshl_b32 s18, s15, 5
	s_add_i32 s17, s17, s18
	s_add_u32 s42, s26, 0x5600000
	s_addc_u32 s43, s27, 0
	s_add_u32 s42, s42, s17
	s_addc_u32 s43, s43, 0
	s_lshl_b32 s17, s8, 2
	s_add_u32 s44, s26, 0xee00000
	s_addc_u32 s45, s27, 0
	s_add_u32 s44, s44, s17
	s_addc_u32 s45, s45, 0
	s_cmp_eq_u32 s15, 0
	s_cselect_b32 s58, 1, 0
	s_xor_b32 s59, s6, s9
	s_load_dwordx2 s[46:47], s[0:1], 0x48
	s_load_dwordx2 s[48:49], s[0:1], 0x60
	s_load_dwordx2 s[50:51], s[0:1], 0x78
	s_load_dwordx2 s[52:53], s[0:1], 0x80
	s_load_dwordx2 s[54:55], s[0:1], 0x88
	s_lshl_b32 s17, s8, 8
	s_lshl_b32 s18, s15, 7
	s_add_i32 s19, s17, s18
	v_lshl_add_u32 v198, v217, 4, s19
	s_xor_b32 s18, s18, 128
	s_add_i32 s19, s17, s18
	v_lshl_add_u32 v199, v217, 4, s19
	s_waitcnt lgkmcnt(0)
	s_lshl_b32 s17, s6, 12
	s_add_u32 s46, s46, s17
	s_addc_u32 s47, s47, 0
	s_add_u32 s48, s48, s17
	s_addc_u32 s49, s49, 0
	s_add_u32 s46, s46, 0x2000
	s_addc_u32 s47, s47, 0
	s_add_u32 s48, s48, 0x2000
	s_addc_u32 s49, s49, 0
	s_add_u32 s50, s50, 0x1000
	s_addc_u32 s51, s51, 0
	s_add_u32 s52, s52, 0x1000
	s_addc_u32 s53, s53, 0
	s_add_u32 s54, s54, 0x1000
	s_addc_u32 s55, s55, 0
	global_load_dwordx4 v[32:35], v198, s[46:47] offset:0
	global_load_dwordx4 v[40:43], v198, s[48:49] offset:0
	global_load_dwordx4 v[64:67], v198, s[52:53] offset:0
	global_load_dwordx4 v[36:39], v198, s[46:47] offset:64
	global_load_dwordx4 v[44:47], v198, s[48:49] offset:64
	global_load_dwordx4 v[68:71], v198, s[52:53] offset:64
	global_load_dwordx4 v[48:51], v198, s[50:51] offset:0
	global_load_dwordx4 v[72:75], v198, s[54:55] offset:0
	global_load_dwordx4 v[52:55], v198, s[50:51] offset:64
	global_load_dwordx4 v[76:79], v198, s[54:55] offset:64
	global_load_dwordx4 v[56:59], v199, s[50:51] offset:0
	global_load_dwordx4 v[80:83], v199, s[54:55] offset:0
	global_load_dwordx4 v[60:63], v199, s[50:51] offset:64
	global_load_dwordx4 v[84:87], v199, s[54:55] offset:64
	s_lshl_b32 s17, s8, 6
	s_lshl_b32 s18, s15, 5
	s_add_i32 s17, s17, s18
	v_add_u32_e32 v200, s17, v196
	v_lshlrev_b32_e32 v200, 7, v200
	v_add_u32_e32 v200, v200, v221
	s_lshl_b32 s17, s6, 17
	s_add_u32 s46, s26, 0x200000
	s_addc_u32 s47, s27, 0
	s_add_u32 s46, s46, s17
	s_addc_u32 s47, s47, 0
	s_add_u32 s48, s46, 0x40000
	s_addc_u32 s49, s47, 0
	global_load_dwordx4 v[0:3], v200, s[46:47] offset:0
	global_load_dwordx4 v[16:19], v200, s[48:49] offset:0
	global_load_dwordx4 v[4:7], v200, s[46:47] offset:64
	global_load_dwordx4 v[20:23], v200, s[48:49] offset:64
	global_load_dwordx4 v[8:11], v200, s[46:47] offset:2048
	global_load_dwordx4 v[24:27], v200, s[48:49] offset:2048
	global_load_dwordx4 v[12:15], v200, s[46:47] offset:2112
	global_load_dwordx4 v[28:31], v200, s[48:49] offset:2112
	s_mov_b32 s10, 0
	s_mov_b32 s11, 0
	s_lshl_b32 s17, s10, 5
	s_cmp_lt_u32 s10, 8
	s_movk_i32 s18, 0x11ff
	s_cselect_b32 s18, 0xff, s18
	s_sub_i32 s18, s18, s17
	s_cmp_eq_u32 s6, 0
	s_cselect_b32 s17, s17, s18
	s_add_i32 s17, s17, s16
	v_add_u32_e32 v231, s17, v218
	v_lshl_add_u32 v226, v231, 9, v221
	v_lshl_add_u32 v227, v231, 11, v219
	v_lshl_add_u32 v228, v231, 11, v220
	v_lshlrev_b32_e32 v229, 3, v217
	v_lshl_add_u32 v229, v231, 11, v229
	v_lshlrev_b32_e32 v230, 6, v231
	global_load_dwordx4 v[88:91], v226, s[20:21]
	global_load_dwordx4 v[92:95], v226, s[20:21] offset:64
	global_load_dwordx4 v[96:99], v226, s[20:21] offset:256
	global_load_dwordx4 v[100:103], v226, s[20:21] offset:320
	global_load_dwordx2 v[104:105], v227, s[22:23] offset:0
	global_load_dwordx2 v[106:107], v227, s[22:23] offset:32
	global_load_dwordx2 v[108:109], v228, s[22:23] offset:0
	global_load_dwordx2 v[110:111], v228, s[22:23] offset:32
	global_load_dwordx2 v[112:113], v227, s[24:25] offset:0
	global_load_dwordx2 v[114:115], v227, s[24:25] offset:32
	global_load_dwordx2 v[116:117], v228, s[24:25] offset:0
	global_load_dwordx2 v[118:119], v228, s[24:25] offset:32
	global_load_dwordx2 v[120:121], v229, s[42:43]
	v_mov_b32_e32 v224, v222
	v_mov_b32_e32 v225, v223
	v_mov_b32_e32 v202, v230
	s_and_b32 s17, s10, 3
	s_cmp_eq_u32 s17, s59
	s_cselect_b32 s32, s58, 0
	s_waitcnt vmcnt(0)
; __device__ __forceinline__ float sigm(float x) { return __builtin_amdgcn_rcpf(1.f + __expf(-x)); }
; template <int CTRL> __device__ __forceinline__ float dppf(float x) { return __builtin_bit_cast(float, __builtin_amdgcn_update_dpp(0, __builtin_bit_cast(int, x), CTRL, 0xF, 0xF, false)); }
; #define LDS_BAR() asm volatile("s_waitcnt lgkmcnt(0)\n\ts_barrier" ::: "memory")
; __device__ __forceinline__ void phase_rwkv_scan(const Fr& F, int jr) {
;     ...
;                 for (int kst = 0; kst < 2; ++kst) { cw = __builtin_amdgcn_mfma_f32_16x16x32_bf16(Aw[kst], Bw[hh][kst], cw, 0, 0, 0); ca = __builtin_amdgcn_mfma_f32_16x16x32_bf16(Aa[kst], Ba[hh][kst], ca, 0, 0, 0); }
; #pragma unroll
;                 for (int reg = 0; reg < 4; ++reg) { const int pp = pt * 16 + lq * 4 + reg;
;                     Wv[pp * 64 + hk] = __expf(-0.60653066f * sigm(w0v[hh] + cw[reg]));
;                     Av[pp * 64 + hk] = sigm(a0v[hh] + ca[reg]); }
;             }
;             LDS_BAR();
;             {
;                 const float kr[8] = {lo_bf(kw.x), hi_bf(kw.x), lo_bf(kw.y), hi_bf(kw.y), lo_bf(kw.z), hi_bf(kw.z), lo_bf(kw.w), hi_bf(kw.w)};
;                 const float rr[8] = {lo_bf(rw.x), hi_bf(rw.x), lo_bf(rw.y), hi_bf(rw.y), lo_bf(rw.z), hi_bf(rw.z), lo_bf(rw.w), hi_bf(rw.w)};
;                 float kq[8]; float ss = 0.f, bon = 0.f;
; #pragma unroll
;                 for (int i = 0; i < 8; ++i) { kq[i] = kr[i] * kkc[i]; ss += kq[i] * kq[i]; bon += rr[i] * kr[i] * rkc[i]; }
;                 ss += dppf<0xB1>(ss); ss += dppf<0x4E>(ss); ss += dppf<0x141>(ss); bon += dppf<0xB1>(bon); bon += dppf<0x4E>(bon); bon += dppf<0x141>(bon);
;                 if (s == 0 && half == 0 && j8 == 0) Bon[((size_t)b * TB + tokof(s, chunk * 64 + p2)) * 16 + h] = bon;
	v_mfma_f32_16x16x32_bf16 v[136:139], v[0:3], v[88:91], 0
	v_mfma_f32_16x16x32_bf16 v[136:139], v[4:7], v[92:95], v[136:139]
	v_mfma_f32_16x16x32_bf16 v[140:143], v[8:11], v[88:91], 0
	v_mfma_f32_16x16x32_bf16 v[140:143], v[12:15], v[92:95], v[140:143]
	v_mfma_f32_16x16x32_bf16 v[144:147], v[16:19], v[96:99], 0
	v_mfma_f32_16x16x32_bf16 v[144:147], v[20:23], v[100:103], v[144:147]
	v_mfma_f32_16x16x32_bf16 v[148:151], v[24:27], v[96:99], 0
	v_mfma_f32_16x16x32_bf16 v[148:151], v[28:31], v[100:103], v[148:151]
	v_lshlrev_b32_e32 v152, 16, v104
	v_and_b32_e32 v153, 0xffff0000, v104
	v_lshlrev_b32_e32 v154, 16, v105
	v_and_b32_e32 v155, 0xffff0000, v105
	v_lshlrev_b32_e32 v156, 16, v106
	v_and_b32_e32 v157, 0xffff0000, v106
	v_lshlrev_b32_e32 v158, 16, v107
	v_and_b32_e32 v159, 0xffff0000, v107
	v_lshlrev_b32_e32 v160, 16, v108
	v_and_b32_e32 v161, 0xffff0000, v108
	v_lshlrev_b32_e32 v162, 16, v109
	v_and_b32_e32 v163, 0xffff0000, v109
	v_lshlrev_b32_e32 v164, 16, v110
	v_and_b32_e32 v165, 0xffff0000, v110
	v_lshlrev_b32_e32 v166, 16, v111
	v_and_b32_e32 v167, 0xffff0000, v111
	v_lshlrev_b32_e32 v168, 16, v112
	v_and_b32_e32 v169, 0xffff0000, v112
	v_lshlrev_b32_e32 v170, 16, v113
	v_and_b32_e32 v171, 0xffff0000, v113
	v_lshlrev_b32_e32 v172, 16, v114
	v_and_b32_e32 v173, 0xffff0000, v114
	v_lshlrev_b32_e32 v174, 16, v115
	v_and_b32_e32 v175, 0xffff0000, v115
	v_lshlrev_b32_e32 v192, 16, v120
	v_and_b32_e32 v193, 0xffff0000, v120
	v_lshlrev_b32_e32 v194, 16, v121
	v_and_b32_e32 v195, 0xffff0000, v121
	v_pk_mul_f32 v[176:177], v[152:153], v[48:49]
	v_pk_mul_f32 v[178:179], v[154:155], v[50:51]
	v_pk_mul_f32 v[180:181], v[156:157], v[52:53]
	v_pk_mul_f32 v[182:183], v[158:159], v[54:55]
	v_pk_mul_f32 v[184:185], v[160:161], v[56:57]
	v_pk_mul_f32 v[186:187], v[162:163], v[58:59]
	v_pk_mul_f32 v[188:189], v[164:165], v[60:61]
	v_pk_mul_f32 v[190:191], v[166:167], v[62:63]
	v_pk_mul_f32 v[196:197], v[176:177], v[176:177]
	v_pk_mul_f32 v[198:199], v[178:179], v[178:179]
	v_pk_fma_f32 v[196:197], v[180:181], v[180:181], v[196:197]
	v_pk_fma_f32 v[198:199], v[182:183], v[182:183], v[198:199]
	v_pk_fma_f32 v[196:197], v[184:185], v[184:185], v[196:197]
	v_pk_fma_f32 v[198:199], v[186:187], v[186:187], v[198:199]
	v_pk_fma_f32 v[196:197], v[188:189], v[188:189], v[196:197]
	v_pk_fma_f32 v[198:199], v[190:191], v[190:191], v[198:199]
	s_nop 0
	v_pk_add_f32 v[196:197], v[196:197], v[198:199]
	s_cmp_eq_u32 s32, 0
	s_cbranch_scc1 .Lrw3_hnbc0
	v_mul_f32_e32 v208, v168, v152
	v_mul_f32_e32 v209, v169, v153
	v_mul_f32_e32 v210, v170, v154
	v_mul_f32_e32 v211, v171, v155
	v_mul_f32_e32 v234, v72, v208
	v_fmac_f32_e32 v234, v73, v209
	v_fmac_f32_e32 v234, v74, v210
	v_fmac_f32_e32 v234, v75, v211
	v_mul_f32_e32 v208, v172, v156
	v_mul_f32_e32 v209, v173, v157
	v_mul_f32_e32 v210, v174, v158
	v_mul_f32_e32 v211, v175, v159
	v_fmac_f32_e32 v234, v76, v208
	v_fmac_f32_e32 v234, v77, v209
	v_fmac_f32_e32 v234, v78, v210
	v_fmac_f32_e32 v234, v79, v211
	v_lshlrev_b32_e32 v204, 16, v116
	v_and_b32_e32 v205, 0xffff0000, v116
	v_lshlrev_b32_e32 v206, 16, v117
	v_and_b32_e32 v207, 0xffff0000, v117
	v_mul_f32_e32 v208, v204, v160
	v_mul_f32_e32 v209, v205, v161
	v_mul_f32_e32 v210, v206, v162
	v_mul_f32_e32 v211, v207, v163
	v_fmac_f32_e32 v234, v80, v208
	v_fmac_f32_e32 v234, v81, v209
	v_fmac_f32_e32 v234, v82, v210
	v_fmac_f32_e32 v234, v83, v211
	v_lshlrev_b32_e32 v204, 16, v118
	v_and_b32_e32 v205, 0xffff0000, v118
	v_lshlrev_b32_e32 v206, 16, v119
	v_and_b32_e32 v207, 0xffff0000, v119
	v_mul_f32_e32 v208, v204, v164
	v_mul_f32_e32 v209, v205, v165
	v_mul_f32_e32 v210, v206, v166
	v_mul_f32_e32 v211, v207, v167
	v_fmac_f32_e32 v234, v84, v208
	v_fmac_f32_e32 v234, v85, v209
	v_fmac_f32_e32 v234, v86, v210
	v_fmac_f32_e32 v234, v87, v211
